# phase 9 pair loop: max tree as two v_max3 chains without canonicalising ops; second p-masking dropped by clamping the exponent reference to max(mrun,-2^96)
# speedup vs baseline: 1.0041x; 1.0011x over previous
; #define LAS __attribute__((address_space(3)))
; __device__ __forceinline__ int crow(int r, int hi) { return (r & 3) + 8 * (r >> 2) + 4 * hi; }
;     ...
;     auto QK = [&](const LAS unsigned char* sbase, f32x16& s0, f32x16& s1) {
;         const LAS unsigned char* kb = sbase + r32 * KSTR; const int kc0 = (koff >> 3) + hi;
; #pragma unroll
;         for (int r = 0; r < 16; ++r) { s0[r] = 0.f; s1[r] = 0.f; }
; #pragma unroll
;         for (int kh = 0; kh < NKS; kh += 4) {
;             bf16x8 ka[4][2];
; #pragma unroll
;             for (int ks = 0; ks < 4; ++ks) { const int ko = ((kc0 + 2 * (kh + ks)) ^ ksw) << 4; ka[ks][0] = *(const LAS bf16x8*)(kb + ko); ka[ks][1] = *(const LAS bf16x8*)(kb + 32 * KSTR + ko); }
;             __builtin_amdgcn_s_setprio(1);
; #pragma unroll
;             for (int ks = 0; ks < 4; ++ks) { s0 = __builtin_amdgcn_mfma_f32_32x32x16_bf16(ka[ks][0], qf[kh + ks], s0, 0, 0, 0); s1 = __builtin_amdgcn_mfma_f32_32x32x16_bf16(ka[ks][1], qf[kh + ks], s1, 0, 0, 0); }
;             __builtin_amdgcn_s_setprio(0);
;         }
;     };
;     auto SM = [&](unsigned w0, unsigned w1, f32x16& s0, f32x16& s1, bf16x8 (&pb)[2][2]) {
;         if (LAYER == 1) {
; #pragma unroll
;             for (int r = 0; r < 16; ++r) { const int kv = crow(r, hi); if (!((w0 >> kv) & 1u)) s0[r] = -1e30f; if (!((w1 >> kv) & 1u)) s1[r] = -1e30f; } }
;         float mx = fmaxf(s0[0], s1[0]);
; #pragma unroll
;         for (int r = 1; r < 16; ++r) mx = fmaxf(mx, fmaxf(s0[r], s1[r]));
;         mx = fmaxf(mx, __shfl_xor(mx, 32));
.LBB0_2110:
	s_bitcmp1_b32 s4, 0
	s_cselect_b32 s0, 0x10400, 0
	s_add_i32 s0, s0, 0
	v_add_u32_e32 v82, s0, v172
	v_add_u32_e32 v83, 0x10200, v82
	s_waitcnt lgkmcnt(0)
	ds_read_b64 v[156:157], v83
	v_add_u32_e32 v83, s0, v173
	v_add_u32_e32 v84, s0, v171
	s_cmp_gt_i32 s85, s90
	v_add_u32_e32 v214, v83, v174
	v_add_u32_e32 v213, v83, v175
	v_add_u32_e32 v212, v83, v176
	v_add_u32_e32 v211, v83, v177
	v_add_u32_e32 v210, v83, v178
	v_add_u32_e32 v209, v83, v179
	v_add_u32_e32 v208, v83, v180
	v_add_u32_e32 v207, v83, v181
	v_add_u32_e32 v155, v84, v161
	v_add_u32_e32 v199, v84, v162
	v_add_u32_e32 v200, v84, v163
	v_add_u32_e32 v201, v84, v166
	v_add_u32_e32 v202, v84, v167
	v_add_u32_e32 v203, v84, v168
	v_add_u32_e32 v204, v84, v169
	v_add_u32_e32 v205, v84, v170
	s_cbranch_scc1 .LBB0_2114
	v_add_u32_e32 v82, 0x10000, v82
	ds_read_b64 v[240:241], v82
	ds_read_b128 v[82:85], v214
	ds_read_b128 v[98:101], v214 offset:8192
	ds_read_b128 v[102:105], v213
	ds_read_b128 v[134:137], v213 offset:8192
	ds_read_b128 v[106:109], v212
	ds_read_b128 v[138:141], v212 offset:8192
	ds_read_b128 v[110:113], v211
	ds_read_b128 v[216:219], v211 offset:8192
	s_setprio 1
	s_waitcnt lgkmcnt(0)
	v_mfma_f32_32x32x16_bf16 v[82:97], v[82:85], v[4:7], 0
	v_mfma_f32_32x32x16_bf16 v[82:97], v[102:105], v[8:11], v[82:97]
	v_mfma_f32_32x32x16_bf16 v[82:97], v[106:109], v[12:15], v[82:97]
	v_mfma_f32_32x32x16_bf16 v[82:97], v[110:113], v[114:117], v[82:97]
	s_setprio 0
	ds_read_b128 v[102:105], v210
	ds_read_b128 v[224:227], v210 offset:8192
	ds_read_b128 v[106:109], v209
	ds_read_b128 v[228:231], v209 offset:8192
	ds_read_b128 v[110:113], v208
	ds_read_b128 v[232:235], v208 offset:8192
	ds_read_b128 v[220:223], v207
	ds_read_b128 v[236:239], v207 offset:8192
	s_setprio 1
	s_waitcnt lgkmcnt(0)
	v_mfma_f32_32x32x16_bf16 v[82:97], v[102:105], v[118:121], v[82:97]
	v_mfma_f32_32x32x16_bf16 v[82:97], v[106:109], v[122:125], v[82:97]
	v_mfma_f32_32x32x16_bf16 v[82:97], v[110:113], v[126:129], v[82:97]
	v_mfma_f32_32x32x16_bf16 v[82:97], v[220:223], v[130:133], v[82:97]
	s_setprio 0
	v_mfma_f32_32x32x16_bf16 v[98:113], v[98:101], v[4:7], 0
	v_and_b32_e32 v215, v240, v182
	v_cmp_eq_u32_e64 s[20:21], 0, v215
	v_and_b32_e32 v221, v240, v183
	v_cmp_eq_u32_e64 s[10:11], 0, v221
	s_nop 5
	v_cndmask_b32_e64 v220, v82, v158, s[20:21]
	v_and_b32_e32 v82, v241, v183
	v_cmp_eq_u32_e64 s[66:67], 0, v82
	v_mfma_f32_32x32x16_bf16 v[98:113], v[134:137], v[8:11], v[98:113]
	v_and_b32_e32 v82, v240, v191
	v_cmp_eq_u32_e64 s[50:51], 0, v82
	v_and_b32_e32 v82, v241, v191
	v_cmp_eq_u32_e64 s[52:53], 0, v82
	v_and_b32_e32 v82, v240, v193
	v_cmp_eq_u32_e64 s[46:47], 0, v82
	v_and_b32_e32 v82, v241, v193
	v_mfma_f32_32x32x16_bf16 v[98:113], v[138:141], v[12:15], v[98:113]
	v_cmp_eq_u32_e64 s[48:49], 0, v82
	v_and_b32_e32 v82, v240, v194
	v_cmp_eq_u32_e64 s[40:41], 0, v82
	v_and_b32_e32 v82, v241, v194
	v_cmp_eq_u32_e64 s[42:43], 0, v82
	v_and_b32_e32 v82, v240, v195
	v_cmp_eq_u32_e64 s[36:37], 0, v82
	v_mfma_f32_32x32x16_bf16 v[98:113], v[216:219], v[114:117], v[98:113]
	v_and_b32_e32 v82, v241, v195
	v_cmp_eq_u32_e64 s[38:39], 0, v82
	v_and_b32_e32 v82, v240, v196
	v_cmp_eq_u32_e64 s[30:31], 0, v82
	v_and_b32_e32 v82, v241, v196
	v_cmp_eq_u32_e64 s[34:35], 0, v82
	v_and_b32_e32 v82, v240, v197
	v_mfma_f32_32x32x16_bf16 v[98:113], v[224:227], v[118:121], v[98:113]
	v_cndmask_b32_e64 v218, v83, v158, s[10:11]
	v_and_b32_e32 v83, v240, v184
	v_cmp_eq_u32_e64 s[26:27], 0, v82
	v_and_b32_e32 v82, v241, v197
	v_and_b32_e32 v242, v241, v184
	v_cmp_eq_u32_e64 s[18:19], 0, v83
	v_cmp_eq_u32_e64 s[28:29], 0, v82
	v_mfma_f32_32x32x16_bf16 v[98:113], v[228:231], v[122:125], v[98:113]
	v_and_b32_e32 v82, v240, v198
	v_and_b32_e32 v215, v240, v185
	v_cndmask_b32_e64 v222, v84, v158, s[18:19]
	v_and_b32_e32 v83, v241, v185
	v_and_b32_e32 v84, v240, v186
	v_cmp_eq_u32_e64 s[64:65], 0, v242
	v_cmp_eq_u32_e64 s[22:23], 0, v82
	v_mfma_f32_32x32x16_bf16 v[98:113], v[232:235], v[126:129], v[98:113]
	v_and_b32_e32 v82, v241, v198
	v_and_b32_e32 v223, v241, v182
	v_cmp_eq_u32_e64 s[8:9], 0, v215
	v_cmp_eq_u32_e64 s[16:17], 0, v84
	v_and_b32_e32 v84, v241, v187
	v_cmp_eq_u32_e64 s[62:63], 0, v83
	v_cmp_eq_u32_e64 s[24:25], 0, v82
	v_mfma_f32_32x32x16_bf16 v[98:113], v[236:239], v[130:133], v[98:113]
	s_nop 0
	v_cndmask_b32_e64 v217, v85, v158, s[8:9]
	v_and_b32_e32 v85, v241, v186
	v_cmp_eq_u32_e64 s[68:69], 0, v223
	v_cmp_eq_u32_e64 s[58:59], 0, v84
	s_nop 0
	v_and_b32_e32 v215, v240, v187
	s_nop 4
	v_cndmask_b32_e64 v230, v99, v158, s[66:67]
	v_cndmask_b32_e64 v229, v100, v158, s[64:65]
	v_cndmask_b32_e64 v228, v101, v158, s[62:63]
	v_cndmask_b32_e64 v231, v98, v158, s[68:69]
	v_cmp_eq_u32_e64 s[60:61], 0, v85
	v_cndmask_b32_e64 v221, v86, v158, s[16:17]
	v_cmp_eq_u32_e64 s[4:5], 0, v215
	v_cndmask_b32_e64 v227, v102, v158, s[60:61]
	v_cndmask_b32_e64 v215, v87, v158, s[4:5]
	v_and_b32_e32 v86, v240, v188
	v_and_b32_e32 v87, v241, v188
	v_cndmask_b32_e64 v226, v103, v158, s[58:59]
	v_and_b32_e32 v216, v240, v189
	v_cmp_eq_u32_e64 s[14:15], 0, v86
	v_and_b32_e32 v86, v241, v189
	v_cmp_eq_u32_e64 s[56:57], 0, v87
	v_cndmask_b32_e64 v219, v88, v158, s[14:15]
	v_cmp_eq_u32_e64 s[6:7], 0, v216
	v_cndmask_b32_e64 v225, v104, v158, s[56:57]
	v_cmp_eq_u32_e64 s[54:55], 0, v86
	v_cndmask_b32_e64 v216, v89, v158, s[6:7]
	v_and_b32_e32 v88, v240, v190
	v_and_b32_e32 v89, v241, v190
	v_cndmask_b32_e64 v223, v105, v158, s[54:55]
	v_cmp_eq_u32_e64 s[12:13], 0, v88
	v_cmp_eq_u32_e64 s[44:45], 0, v89
	v_cndmask_b32_e64 v90, v90, v158, s[12:13]
	v_cndmask_b32_e64 v224, v106, v158, s[44:45]
	v_cndmask_b32_e64 v105, v91, v158, s[50:51]
	v_cndmask_b32_e64 v106, v107, v158, s[52:53]
	v_cndmask_b32_e64 v103, v92, v158, s[46:47]
	v_cndmask_b32_e64 v104, v108, v158, s[48:49]
	v_cndmask_b32_e64 v101, v93, v158, s[40:41]
	v_cndmask_b32_e64 v102, v109, v158, s[42:43]
	v_cndmask_b32_e64 v99, v94, v158, s[36:37]
	v_cndmask_b32_e64 v100, v110, v158, s[38:39]
	v_cndmask_b32_e64 v95, v95, v158, s[30:31]
	v_cndmask_b32_e64 v98, v111, v158, s[34:35]
	v_cndmask_b32_e64 v93, v96, v158, s[26:27]
	v_cndmask_b32_e64 v94, v112, v158, s[28:29]
	v_cndmask_b32_e64 v91, v97, v158, s[22:23]
	v_cndmask_b32_e64 v92, v113, v158, s[24:25]
	v_max3_f32 v96, v220, v218, v222
	v_max3_f32 v247, v217, v230, v229
	v_max3_f32 v96, v96, v228, v231
	v_max3_f32 v247, v247, v221, v227
	v_max3_f32 v96, v96, v215, v226
	v_max3_f32 v247, v247, v219, v225
	v_max3_f32 v96, v96, v216, v223
	v_max3_f32 v247, v247, v90, v224
	v_max3_f32 v96, v96, v105, v106
	v_max3_f32 v247, v247, v103, v104
	v_max3_f32 v96, v96, v101, v102
	v_max3_f32 v247, v247, v99, v100
	v_max3_f32 v96, v96, v95, v98
	v_max3_f32 v247, v247, v93, v94
	v_max3_f32 v96, v96, v91, v92
	v_max_f32_e32 v96, v96, v247
	s_waitcnt vmcnt(0)
; __device__ __forceinline__ int crow(int r, int hi) { return (r & 3) + 8 * (r >> 2) + 4 * hi; }
;     ...
;         mx = fmaxf(mx, __shfl_xor(mx, 32));
;         const bool need = mx > mrun + 8.f;
;         if (__any(need)) { const float mnew = need ? mx : mrun, alpha = __builtin_amdgcn_exp2f(mrun - mnew); mrun = mnew; lrun *= alpha;
; #pragma unroll
;             for (int d = 0; d < 4; ++d)
; #pragma unroll
;                 for (int r = 0; r < 16; ++r) o[d][r] *= alpha; }
;         float rsa[4] = {0.f, 0.f, 0.f, 0.f};
; #pragma unroll
;         for (int r = 0; r < 16; ++r) { float p0 = __builtin_amdgcn_exp2f(s0[r] - mrun), p1 = __builtin_amdgcn_exp2f(s1[r] - mrun);
;             if (LAYER == 1) { const int kv = crow(r, hi); p0 = ((w0 >> kv) & 1u) ? p0 : 0.f; p1 = ((w1 >> kv) & 1u) ? p1 : 0.f; }
;             s0[r] = p0; s1[r] = p1; rsa[r & 3] += p0 + p1; }
;         lrun += (rsa[0] + rsa[1]) + (rsa[2] + rsa[3]);
	ds_read_b64_tr_b16 v[138:139], v155 offset:16384
	ds_read_b64_tr_b16 v[140:141], v199 offset:18432
	ds_read_b64_tr_b16 v[134:135], v200 offset:16384
	ds_read_b64_tr_b16 v[136:137], v201 offset:18432
	v_mov_b32_e32 v246, v96
	v_mov_b32_e32 v247, v96
	ds_read_b64_tr_b16 v[86:87], v202 offset:16384
	ds_read_b64_tr_b16 v[88:89], v203 offset:18432
	ds_read_b64_tr_b16 v[82:83], v204 offset:16384
	ds_read_b64_tr_b16 v[84:85], v205 offset:18432
	v_permlane32_swap_b32_e32 v246, v247
	v_max3_f32 v96, v96, v246, v247
	v_add_f32_e32 v97, 0x41000000, v206
	v_cmp_gt_f32_e32 vcc, v96, v97
	s_cbranch_vccz .LBB0_2113
	s_nop 0
	v_cndmask_b32_e32 v97, v206, v96, vcc
	v_sub_f32_e32 v96, v206, v97
	v_exp_f32_e32 v96, v96
	v_mov_b32_e32 v206, v97
	v_mul_f32_e32 v192, v192, v96
	v_pk_mul_f32 v[80:81], v[80:81], v[96:97] op_sel_hi:[1,0]
	v_pk_mul_f32 v[78:79], v[78:79], v[96:97] op_sel_hi:[1,0]
	v_pk_mul_f32 v[76:77], v[76:77], v[96:97] op_sel_hi:[1,0]
	v_pk_mul_f32 v[74:75], v[74:75], v[96:97] op_sel_hi:[1,0]
	v_pk_mul_f32 v[72:73], v[72:73], v[96:97] op_sel_hi:[1,0]
	v_pk_mul_f32 v[70:71], v[70:71], v[96:97] op_sel_hi:[1,0]
	v_pk_mul_f32 v[68:69], v[68:69], v[96:97] op_sel_hi:[1,0]
	v_pk_mul_f32 v[66:67], v[66:67], v[96:97] op_sel_hi:[1,0]
	v_pk_mul_f32 v[64:65], v[64:65], v[96:97] op_sel_hi:[1,0]
	v_pk_mul_f32 v[62:63], v[62:63], v[96:97] op_sel_hi:[1,0]
	v_pk_mul_f32 v[60:61], v[60:61], v[96:97] op_sel_hi:[1,0]
	v_pk_mul_f32 v[58:59], v[58:59], v[96:97] op_sel_hi:[1,0]
	v_pk_mul_f32 v[56:57], v[56:57], v[96:97] op_sel_hi:[1,0]
	v_pk_mul_f32 v[54:55], v[54:55], v[96:97] op_sel_hi:[1,0]
	v_pk_mul_f32 v[52:53], v[52:53], v[96:97] op_sel_hi:[1,0]
	v_pk_mul_f32 v[50:51], v[50:51], v[96:97] op_sel_hi:[1,0]
	v_pk_mul_f32 v[48:49], v[48:49], v[96:97] op_sel_hi:[1,0]
	v_pk_mul_f32 v[46:47], v[46:47], v[96:97] op_sel_hi:[1,0]
	v_pk_mul_f32 v[44:45], v[44:45], v[96:97] op_sel_hi:[1,0]
	v_pk_mul_f32 v[42:43], v[42:43], v[96:97] op_sel_hi:[1,0]
	v_pk_mul_f32 v[40:41], v[40:41], v[96:97] op_sel_hi:[1,0]
	v_pk_mul_f32 v[38:39], v[38:39], v[96:97] op_sel_hi:[1,0]
	v_pk_mul_f32 v[36:37], v[36:37], v[96:97] op_sel_hi:[1,0]
	v_pk_mul_f32 v[34:35], v[34:35], v[96:97] op_sel_hi:[1,0]
	v_pk_mul_f32 v[32:33], v[32:33], v[96:97] op_sel_hi:[1,0]
	v_pk_mul_f32 v[30:31], v[30:31], v[96:97] op_sel_hi:[1,0]
	v_pk_mul_f32 v[28:29], v[28:29], v[96:97] op_sel_hi:[1,0]
	v_pk_mul_f32 v[26:27], v[26:27], v[96:97] op_sel_hi:[1,0]
	v_pk_mul_f32 v[24:25], v[24:25], v[96:97] op_sel_hi:[1,0]
	v_pk_mul_f32 v[22:23], v[22:23], v[96:97] op_sel_hi:[1,0]
	v_pk_mul_f32 v[20:21], v[20:21], v[96:97] op_sel_hi:[1,0]
	v_pk_mul_f32 v[18:19], v[18:19], v[96:97] op_sel_hi:[1,0]
.LBB0_2113:
	v_max_f32_e32 v246, 0xef800000, v206
	v_sub_f32_e32 v96, v220, v246
	v_sub_f32_e32 v97, v231, v246
	v_exp_f32_e32 v96, v96
	v_exp_f32_e32 v97, v97
	v_sub_f32_e32 v107, v218, v246
	v_sub_f32_e32 v108, v230, v246
	v_sub_f32_e32 v220, v221, v246
	v_sub_f32_e32 v221, v227, v246
	v_exp_f32_e32 v107, v107
	v_exp_f32_e32 v108, v108
	v_sub_f32_e32 v110, v222, v246
	v_sub_f32_e32 v111, v229, v246
	v_exp_f32_e32 v220, v220
	v_exp_f32_e32 v221, v221
	v_sub_f32_e32 v215, v215, v246
	v_sub_f32_e32 v226, v226, v246
	v_exp_f32_e32 v110, v110
	v_exp_f32_e32 v111, v111
	v_sub_f32_e32 v113, v217, v246
	v_sub_f32_e32 v217, v228, v246
	v_exp_f32_e32 v215, v215
	v_exp_f32_e32 v226, v226
	v_sub_f32_e32 v219, v219, v246
	v_sub_f32_e32 v225, v225, v246
	v_exp_f32_e32 v113, v113
	v_exp_f32_e32 v217, v217
	v_exp_f32_e32 v219, v219
	v_exp_f32_e32 v225, v225
	v_sub_f32_e32 v216, v216, v246
	v_sub_f32_e32 v223, v223, v246
	v_exp_f32_e32 v216, v216
	v_exp_f32_e32 v223, v223
	v_add_f32_e32 v109, v96, v97
	v_sub_f32_e32 v90, v90, v246
	v_add_f32_e32 v109, 0, v109
	v_add_f32_e32 v112, v107, v108
	v_add_f32_e32 v227, v220, v221
	v_exp_f32_e32 v90, v90
	v_add_f32_e32 v112, 0, v112
	v_add_f32_e32 v218, v110, v111
	v_add_f32_e32 v109, v227, v109
	v_add_f32_e32 v227, v215, v226
	v_add_f32_e32 v218, 0, v218
	v_add_f32_e32 v222, v113, v217
	v_add_f32_e32 v112, v227, v112
	v_add_f32_e32 v227, v219, v225
	v_sub_f32_e32 v224, v224, v246
	v_add_f32_e32 v222, 0, v222
	v_add_f32_e32 v218, v227, v218
	v_exp_f32_e32 v224, v224
	v_add_f32_e32 v227, v216, v223
	v_add_f32_e32 v222, v227, v222
	v_mov_b32_e32 v227, v90
	v_sub_f32_e32 v90, v105, v246
	v_exp_f32_e32 v90, v90
	v_sub_f32_e32 v105, v106, v246
	v_add_f32_e32 v106, v227, v224
	v_add_f32_e32 v106, v106, v109
	v_mov_b32_e32 v109, v90
	v_sub_f32_e32 v90, v103, v246
	v_exp_f32_e32 v228, v105
	v_exp_f32_e32 v105, v90
	v_sub_f32_e32 v103, v104, v246
	v_exp_f32_e32 v229, v103
	v_sub_f32_e32 v90, v101, v246
	v_exp_f32_e32 v103, v90
	v_sub_f32_e32 v101, v102, v246
	v_exp_f32_e32 v230, v101
	v_sub_f32_e32 v90, v99, v246
	v_exp_f32_e32 v101, v90
	v_sub_f32_e32 v99, v100, v246
	v_exp_f32_e32 v99, v99
	v_sub_f32_e32 v90, v95, v246
	v_exp_f32_e32 v90, v90
	v_add_f32_e32 v100, v103, v230
	v_add_f32_e32 v100, v100, v222
	v_mov_b32_e32 v222, v99
	v_sub_f32_e32 v95, v98, v246
	v_exp_f32_e32 v231, v95
	v_add_f32_e32 v98, v101, v222
	v_add_f32_e32 v98, v98, v106
	v_mov_b32_e32 v106, v90
	v_sub_f32_e32 v90, v93, v246
	v_exp_f32_e32 v90, v90
	v_add_f32_e32 v104, v109, v228
	v_sub_f32_e32 v93, v94, v246
	v_add_f32_e32 v104, v104, v112
	v_exp_f32_e32 v232, v93
	v_add_f32_e32 v94, v106, v231
	v_add_f32_e32 v94, v94, v104
	v_mov_b32_e32 v104, v90
	v_sub_f32_e32 v90, v91, v246
	v_sub_f32_e32 v91, v92, v246
	v_exp_f32_e32 v90, v90
	v_exp_f32_e32 v233, v91
	v_add_f32_e32 v102, v105, v229
	v_add_f32_e32 v102, v102, v218
	v_add_f32_e32 v92, v104, v232
	v_add_f32_e32 v92, v92, v102
	v_mov_b32_e32 v102, v90
	v_add_f32_e32 v90, v102, v233
	v_add_f32_e32 v90, v90, v100
	v_add_f32_e32 v91, v98, v94
	v_add_f32_e32 v90, v92, v90
	v_add_f32_e32 v234, v91, v90
	v_cvt_pk_bf16_f32 v90, v96, v107
	v_cvt_pk_bf16_f32 v91, v110, v113
	v_cvt_pk_bf16_f32 v93, v219, v216
	v_cvt_pk_bf16_f32 v94, v97, v108
	v_cvt_pk_bf16_f32 v95, v111, v217
	v_cvt_pk_bf16_f32 v98, v227, v109
	v_cvt_pk_bf16_f32 v99, v105, v103
	v_cvt_pk_bf16_f32 v100, v101, v106
	v_cvt_pk_bf16_f32 v101, v104, v102
	ds_read_b64_tr_b16 v[102:103], v155 offset:20480
	ds_read_b64_tr_b16 v[104:105], v199 offset:22528
	ds_read_b64_tr_b16 v[106:107], v200 offset:20480
	ds_read_b64_tr_b16 v[108:109], v201 offset:22528
	ds_read_b64_tr_b16 v[110:111], v202 offset:20480
	ds_read_b64_tr_b16 v[112:113], v203 offset:22528
	ds_read_b64_tr_b16 v[216:217], v204 offset:20480
	ds_read_b64_tr_b16 v[218:219], v205 offset:22528
	v_cvt_pk_bf16_f32 v92, v220, v215
	v_cvt_pk_bf16_f32 v96, v221, v226
	v_cvt_pk_bf16_f32 v97, v225, v223
	v_cvt_pk_bf16_f32 v220, v224, v228
	v_cvt_pk_bf16_f32 v221, v229, v230
	v_cvt_pk_bf16_f32 v222, v222, v231
	v_cvt_pk_bf16_f32 v223, v232, v233
	s_setprio 1
	s_waitcnt lgkmcnt(12)
; #define ATT_VREAD(dst, q_) do { const LAS char* vp_ = (const LAS char*)vb + (((q_) >> 1) * 32 + 16 * ((q_) & 1)) * VSTR; \
;         _Pragma("unroll") for (int d_ = 0; d_ < 4; ++d_) { dst[d_][0] = vtr(vp_ + voff[d_][0]); dst[d_][1] = vtr(vp_ + 8 * VSTR + voff[d_][1]); } } while (0)
; #define ATT_PV(src, pb_, q_) do { _Pragma("unroll") for (int d_ = 0; d_ < 4; ++d_) { const s16x4 lo_ = src[d_][0], hh_ = src[d_][1]; \
;         const bf16x8 vf_ = (bf16x8){lo_[0], lo_[1], lo_[2], lo_[3], hh_[0], hh_[1], hh_[2], hh_[3]}; o[d_] = __builtin_amdgcn_mfma_f32_32x32x16_bf16(vf_, pb_[(q_) >> 1][(q_) & 1], o[d_], 0, 0, 0); } } while (0)
;     ...
;             if (wka) { vb = sa + KBUF + vlane; ATT_VREAD(vpre, 0); SM(wa0, wa1, a0, a1, pba);
;                 ATT_VREAD(va, 1); __builtin_amdgcn_s_setprio(1); ATT_PV(vpre, pba, 0); __builtin_amdgcn_s_setprio(0);
;                 ATT_VREAD(vbb, 2); __builtin_amdgcn_s_setprio(1); ATT_PV(va, pba, 1); __builtin_amdgcn_s_setprio(0);
;                 ATT_VREAD(va, 3); __builtin_amdgcn_s_setprio(1); ATT_PV(vbb, pba, 2); __builtin_amdgcn_s_setprio(0);
;                 __builtin_amdgcn_s_setprio(1); ATT_PV(va, pba, 3); __builtin_amdgcn_s_setprio(0); }
;             if (LAYER == 1) { if (wkb) QK(sbb, b0, b1); }
	v_mfma_f32_32x32x16_bf16 v[66:81], v[138:141], v[90:93], v[66:81]
	v_add_f32_e32 v192, v192, v234
	v_mfma_f32_32x32x16_bf16 v[50:65], v[134:137], v[90:93], v[50:65]
	s_waitcnt lgkmcnt(10)
	v_mfma_f32_32x32x16_bf16 v[34:49], v[86:89], v[90:93], v[34:49]
	s_waitcnt lgkmcnt(8)
	v_mfma_f32_32x32x16_bf16 v[18:33], v[82:85], v[90:93], v[18:33]
	s_setprio 0
	ds_read_b64_tr_b16 v[82:83], v155 offset:24576
	ds_read_b64_tr_b16 v[84:85], v199 offset:26624
	ds_read_b64_tr_b16 v[86:87], v200 offset:24576
	ds_read_b64_tr_b16 v[88:89], v201 offset:26624
	ds_read_b64_tr_b16 v[90:91], v202 offset:24576
	ds_read_b64_tr_b16 v[92:93], v203 offset:26624
	ds_read_b64_tr_b16 v[134:135], v204 offset:24576
	ds_read_b64_tr_b16 v[136:137], v205 offset:26624
	s_setprio 1
	s_waitcnt lgkmcnt(14)
	v_mfma_f32_32x32x16_bf16 v[66:81], v[102:105], v[98:101], v[66:81]
	s_waitcnt lgkmcnt(12)
	v_mfma_f32_32x32x16_bf16 v[50:65], v[106:109], v[98:101], v[50:65]
	s_waitcnt lgkmcnt(10)
	v_mfma_f32_32x32x16_bf16 v[34:49], v[110:113], v[98:101], v[34:49]
	s_waitcnt lgkmcnt(8)
	v_mfma_f32_32x32x16_bf16 v[18:33], v[216:219], v[98:101], v[18:33]
	s_setprio 0
	ds_read_b64_tr_b16 v[98:99], v155 offset:28672
	ds_read_b64_tr_b16 v[100:101], v199 offset:30720
	ds_read_b64_tr_b16 v[102:103], v200 offset:28672
	ds_read_b64_tr_b16 v[104:105], v201 offset:30720
	ds_read_b64_tr_b16 v[106:107], v202 offset:28672
	ds_read_b64_tr_b16 v[108:109], v203 offset:30720
	ds_read_b64_tr_b16 v[110:111], v204 offset:28672
	ds_read_b64_tr_b16 v[112:113], v205 offset:30720
	s_setprio 1
	s_waitcnt lgkmcnt(14)
	v_mfma_f32_32x32x16_bf16 v[66:81], v[82:85], v[94:97], v[66:81]
	s_waitcnt lgkmcnt(12)
	v_mfma_f32_32x32x16_bf16 v[50:65], v[86:89], v[94:97], v[50:65]
	s_waitcnt lgkmcnt(10)
	v_mfma_f32_32x32x16_bf16 v[34:49], v[90:93], v[94:97], v[34:49]
	s_waitcnt lgkmcnt(8)
	v_mfma_f32_32x32x16_bf16 v[18:33], v[134:137], v[94:97], v[18:33]
	s_setprio 0
	s_setprio 1
	s_waitcnt lgkmcnt(6)
	v_mfma_f32_32x32x16_bf16 v[66:81], v[98:101], v[220:223], v[66:81]
	s_waitcnt lgkmcnt(4)
	v_mfma_f32_32x32x16_bf16 v[50:65], v[102:105], v[220:223], v[50:65]
	s_waitcnt lgkmcnt(2)
	v_mfma_f32_32x32x16_bf16 v[34:49], v[106:109], v[220:223], v[34:49]
	s_waitcnt lgkmcnt(0)
	v_mfma_f32_32x32x16_bf16 v[18:33], v[110:113], v[220:223], v[18:33]
	s_setprio 0
.LBB0_2114:
	s_cmp_ge_i32 s85, s90
	s_cbranch_scc1 .LBB0_2118
	ds_read_b128 v[82:85], v214 offset:32768
	ds_read_b128 v[98:101], v214 offset:40960
	ds_read_b128 v[102:105], v213 offset:32768
	ds_read_b128 v[134:137], v213 offset:40960
	ds_read_b128 v[106:109], v212 offset:32768
	ds_read_b128 v[138:141], v212 offset:40960
	ds_read_b128 v[110:113], v211 offset:32768
	ds_read_b128 v[214:217], v211 offset:40960
	s_setprio 1
	s_waitcnt lgkmcnt(0)
	v_mfma_f32_32x32x16_bf16 v[82:97], v[82:85], v[4:7], 0
	v_mfma_f32_32x32x16_bf16 v[82:97], v[102:105], v[8:11], v[82:97]
	v_mfma_f32_32x32x16_bf16 v[82:97], v[106:109], v[12:15], v[82:97]
	v_mfma_f32_32x32x16_bf16 v[82:97], v[110:113], v[114:117], v[82:97]
	s_setprio 0
	ds_read_b128 v[102:105], v210 offset:32768
	ds_read_b128 v[218:221], v210 offset:40960
	ds_read_b128 v[106:109], v209 offset:32768
	ds_read_b128 v[222:225], v209 offset:40960
	ds_read_b128 v[110:113], v208 offset:32768
	ds_read_b128 v[226:229], v208 offset:40960
	ds_read_b128 v[208:211], v207 offset:32768
	ds_read_b128 v[230:233], v207 offset:40960
	s_setprio 1
	s_waitcnt lgkmcnt(0)
	v_mfma_f32_32x32x16_bf16 v[82:97], v[102:105], v[118:121], v[82:97]
	v_mfma_f32_32x32x16_bf16 v[82:97], v[106:109], v[122:125], v[82:97]
	v_mfma_f32_32x32x16_bf16 v[82:97], v[110:113], v[126:129], v[82:97]
	v_mfma_f32_32x32x16_bf16 v[82:97], v[208:211], v[130:133], v[82:97]
	s_setprio 0
	v_mfma_f32_32x32x16_bf16 v[98:113], v[98:101], v[4:7], 0
	v_and_b32_e32 v207, v156, v182
	v_cmp_eq_u32_e64 s[20:21], 0, v207
	v_and_b32_e32 v208, v156, v183
	v_cmp_eq_u32_e64 s[10:11], 0, v208
	s_nop 5
	v_cndmask_b32_e64 v212, v82, v158, s[20:21]
	v_and_b32_e32 v82, v157, v183
	v_cmp_eq_u32_e64 s[66:67], 0, v82
	v_mfma_f32_32x32x16_bf16 v[98:113], v[134:137], v[8:11], v[98:113]
	v_and_b32_e32 v82, v156, v191
	v_cmp_eq_u32_e64 s[50:51], 0, v82
	v_and_b32_e32 v82, v157, v191
	v_cmp_eq_u32_e64 s[52:53], 0, v82
	v_and_b32_e32 v82, v156, v193
	v_cmp_eq_u32_e64 s[46:47], 0, v82
	v_and_b32_e32 v82, v157, v193
	v_mfma_f32_32x32x16_bf16 v[98:113], v[138:141], v[12:15], v[98:113]
	v_cmp_eq_u32_e64 s[48:49], 0, v82
	v_and_b32_e32 v82, v156, v194
	v_cmp_eq_u32_e64 s[40:41], 0, v82
	v_and_b32_e32 v82, v157, v194
	v_cmp_eq_u32_e64 s[42:43], 0, v82
	v_and_b32_e32 v82, v156, v195
	v_cmp_eq_u32_e64 s[36:37], 0, v82
	v_mfma_f32_32x32x16_bf16 v[98:113], v[214:217], v[114:117], v[98:113]
	v_and_b32_e32 v82, v157, v195
	v_cmp_eq_u32_e64 s[38:39], 0, v82
	v_and_b32_e32 v82, v156, v196
	v_cmp_eq_u32_e64 s[30:31], 0, v82
	v_and_b32_e32 v82, v157, v196
	v_cmp_eq_u32_e64 s[34:35], 0, v82
	v_and_b32_e32 v82, v156, v197
	v_mfma_f32_32x32x16_bf16 v[98:113], v[218:221], v[118:121], v[98:113]
	v_cndmask_b32_e64 v210, v83, v158, s[10:11]
	v_and_b32_e32 v83, v156, v184
	v_cmp_eq_u32_e64 s[26:27], 0, v82
	v_and_b32_e32 v82, v157, v197
	v_and_b32_e32 v215, v157, v184
	v_cmp_eq_u32_e64 s[18:19], 0, v83
	v_cmp_eq_u32_e64 s[28:29], 0, v82
	v_mfma_f32_32x32x16_bf16 v[98:113], v[222:225], v[122:125], v[98:113]
	v_and_b32_e32 v82, v156, v198
	v_and_b32_e32 v207, v156, v185
	v_cndmask_b32_e64 v214, v84, v158, s[18:19]
	v_and_b32_e32 v83, v157, v185
	v_and_b32_e32 v84, v156, v186
	v_cmp_eq_u32_e64 s[64:65], 0, v215
	v_cmp_eq_u32_e64 s[22:23], 0, v82
	v_mfma_f32_32x32x16_bf16 v[98:113], v[226:229], v[126:129], v[98:113]
	v_and_b32_e32 v82, v157, v198
; __device__ __forceinline__ int crow(int r, int hi) { return (r & 3) + 8 * (r >> 2) + 4 * hi; }
;     ...
;     auto SM = [&](unsigned w0, unsigned w1, f32x16& s0, f32x16& s1, bf16x8 (&pb)[2][2]) {
;         if (LAYER == 1) {
; #pragma unroll
;             for (int r = 0; r < 16; ++r) { const int kv = crow(r, hi); if (!((w0 >> kv) & 1u)) s0[r] = -1e30f; if (!((w1 >> kv) & 1u)) s1[r] = -1e30f; } }
;         float mx = fmaxf(s0[0], s1[0]);
; #pragma unroll
;         for (int r = 1; r < 16; ++r) mx = fmaxf(mx, fmaxf(s0[r], s1[r]));
;         mx = fmaxf(mx, __shfl_xor(mx, 32));
;         const bool need = mx > mrun + 8.f;
;         if (__any(need)) { const float mnew = need ? mx : mrun, alpha = __builtin_amdgcn_exp2f(mrun - mnew); mrun = mnew; lrun *= alpha;
; #pragma unroll
;             for (int d = 0; d < 4; ++d)
; #pragma unroll
;                 for (int r = 0; r < 16; ++r) o[d][r] *= alpha; }
	v_and_b32_e32 v234, v157, v182
	v_cmp_eq_u32_e64 s[8:9], 0, v207
	v_cmp_eq_u32_e64 s[16:17], 0, v84
	v_and_b32_e32 v84, v157, v187
	v_cmp_eq_u32_e64 s[62:63], 0, v83
	v_cmp_eq_u32_e64 s[24:25], 0, v82
	v_mfma_f32_32x32x16_bf16 v[98:113], v[230:233], v[130:133], v[98:113]
	s_nop 0
	v_cndmask_b32_e64 v209, v85, v158, s[8:9]
	v_and_b32_e32 v85, v157, v186
	v_cmp_eq_u32_e64 s[68:69], 0, v234
	v_cmp_eq_u32_e64 s[58:59], 0, v84
	s_nop 0
	v_and_b32_e32 v207, v156, v187
	s_nop 4
	v_cndmask_b32_e64 v222, v99, v158, s[66:67]
	v_cndmask_b32_e64 v221, v100, v158, s[64:65]
	v_cndmask_b32_e64 v220, v101, v158, s[62:63]
	v_cndmask_b32_e64 v223, v98, v158, s[68:69]
	v_cmp_eq_u32_e64 s[60:61], 0, v85
	v_cndmask_b32_e64 v213, v86, v158, s[16:17]
	v_cmp_eq_u32_e64 s[4:5], 0, v207
	v_cndmask_b32_e64 v219, v102, v158, s[60:61]
	v_cndmask_b32_e64 v207, v87, v158, s[4:5]
	v_and_b32_e32 v86, v156, v188
	v_and_b32_e32 v87, v157, v188
	v_cndmask_b32_e64 v218, v103, v158, s[58:59]
	v_and_b32_e32 v208, v156, v189
	v_cmp_eq_u32_e64 s[14:15], 0, v86
	v_and_b32_e32 v86, v157, v189
	v_cmp_eq_u32_e64 s[56:57], 0, v87
	v_cndmask_b32_e64 v211, v88, v158, s[14:15]
	v_cmp_eq_u32_e64 s[6:7], 0, v208
	v_cndmask_b32_e64 v217, v104, v158, s[56:57]
	v_cmp_eq_u32_e64 s[54:55], 0, v86
	v_cndmask_b32_e64 v208, v89, v158, s[6:7]
	v_and_b32_e32 v88, v156, v190
	v_and_b32_e32 v89, v157, v190
	v_cndmask_b32_e64 v215, v105, v158, s[54:55]
	v_cmp_eq_u32_e64 s[12:13], 0, v88
	v_cmp_eq_u32_e64 s[44:45], 0, v89
	v_cndmask_b32_e64 v90, v90, v158, s[12:13]
	v_cndmask_b32_e64 v216, v106, v158, s[44:45]
	v_cndmask_b32_e64 v105, v91, v158, s[50:51]
	v_cndmask_b32_e64 v106, v107, v158, s[52:53]
	v_cndmask_b32_e64 v103, v92, v158, s[46:47]
	v_cndmask_b32_e64 v104, v108, v158, s[48:49]
	v_cndmask_b32_e64 v101, v93, v158, s[40:41]
	v_cndmask_b32_e64 v102, v109, v158, s[42:43]
	v_cndmask_b32_e64 v99, v94, v158, s[36:37]
	v_cndmask_b32_e64 v100, v110, v158, s[38:39]
	v_cndmask_b32_e64 v95, v95, v158, s[30:31]
	v_cndmask_b32_e64 v98, v111, v158, s[34:35]
	v_cndmask_b32_e64 v93, v96, v158, s[26:27]
	v_cndmask_b32_e64 v94, v112, v158, s[28:29]
	v_cndmask_b32_e64 v91, v97, v158, s[22:23]
	v_cndmask_b32_e64 v92, v113, v158, s[24:25]
	v_max3_f32 v96, v212, v210, v214
	v_max3_f32 v247, v209, v222, v221
	v_max3_f32 v96, v96, v220, v223
	v_max3_f32 v247, v247, v213, v219
	v_max3_f32 v96, v96, v207, v218
	v_max3_f32 v247, v247, v211, v217
	v_max3_f32 v96, v96, v208, v215
	v_max3_f32 v247, v247, v90, v216
	v_max3_f32 v96, v96, v105, v106
	v_max3_f32 v247, v247, v103, v104
	v_max3_f32 v96, v96, v101, v102
	v_max3_f32 v247, v247, v99, v100
	v_max3_f32 v96, v96, v95, v98
	v_max3_f32 v247, v247, v93, v94
	v_max3_f32 v96, v96, v91, v92
	v_max_f32_e32 v96, v96, v247
	s_waitcnt vmcnt(0)
	ds_read_b64_tr_b16 v[138:139], v155 offset:49152
	ds_read_b64_tr_b16 v[140:141], v199 offset:51200
	ds_read_b64_tr_b16 v[134:135], v200 offset:49152
	ds_read_b64_tr_b16 v[136:137], v201 offset:51200
	v_mov_b32_e32 v246, v96
	v_mov_b32_e32 v247, v96
	ds_read_b64_tr_b16 v[86:87], v202 offset:49152
	ds_read_b64_tr_b16 v[88:89], v203 offset:51200
	ds_read_b64_tr_b16 v[82:83], v204 offset:49152
	ds_read_b64_tr_b16 v[84:85], v205 offset:51200
	v_permlane32_swap_b32_e32 v246, v247
	v_max3_f32 v96, v96, v246, v247
	v_add_f32_e32 v97, 0x41000000, v206
	v_cmp_gt_f32_e32 vcc, v96, v97
	s_cbranch_vccz .LBB0_2117
	s_nop 0
	v_cndmask_b32_e32 v97, v206, v96, vcc
	v_sub_f32_e32 v96, v206, v97
	v_exp_f32_e32 v96, v96
	v_mov_b32_e32 v206, v97
	v_mul_f32_e32 v192, v192, v96
	v_pk_mul_f32 v[80:81], v[80:81], v[96:97] op_sel_hi:[1,0]
	v_pk_mul_f32 v[78:79], v[78:79], v[96:97] op_sel_hi:[1,0]
	v_pk_mul_f32 v[76:77], v[76:77], v[96:97] op_sel_hi:[1,0]
	v_pk_mul_f32 v[74:75], v[74:75], v[96:97] op_sel_hi:[1,0]
	v_pk_mul_f32 v[72:73], v[72:73], v[96:97] op_sel_hi:[1,0]
	v_pk_mul_f32 v[70:71], v[70:71], v[96:97] op_sel_hi:[1,0]
	v_pk_mul_f32 v[68:69], v[68:69], v[96:97] op_sel_hi:[1,0]
	v_pk_mul_f32 v[66:67], v[66:67], v[96:97] op_sel_hi:[1,0]
	v_pk_mul_f32 v[64:65], v[64:65], v[96:97] op_sel_hi:[1,0]
	v_pk_mul_f32 v[62:63], v[62:63], v[96:97] op_sel_hi:[1,0]
	v_pk_mul_f32 v[60:61], v[60:61], v[96:97] op_sel_hi:[1,0]
	v_pk_mul_f32 v[58:59], v[58:59], v[96:97] op_sel_hi:[1,0]
	v_pk_mul_f32 v[56:57], v[56:57], v[96:97] op_sel_hi:[1,0]
	v_pk_mul_f32 v[54:55], v[54:55], v[96:97] op_sel_hi:[1,0]
	v_pk_mul_f32 v[52:53], v[52:53], v[96:97] op_sel_hi:[1,0]
	v_pk_mul_f32 v[50:51], v[50:51], v[96:97] op_sel_hi:[1,0]
	v_pk_mul_f32 v[48:49], v[48:49], v[96:97] op_sel_hi:[1,0]
	v_pk_mul_f32 v[46:47], v[46:47], v[96:97] op_sel_hi:[1,0]
	v_pk_mul_f32 v[44:45], v[44:45], v[96:97] op_sel_hi:[1,0]
	v_pk_mul_f32 v[42:43], v[42:43], v[96:97] op_sel_hi:[1,0]
	v_pk_mul_f32 v[40:41], v[40:41], v[96:97] op_sel_hi:[1,0]
	v_pk_mul_f32 v[38:39], v[38:39], v[96:97] op_sel_hi:[1,0]
	v_pk_mul_f32 v[36:37], v[36:37], v[96:97] op_sel_hi:[1,0]
	v_pk_mul_f32 v[34:35], v[34:35], v[96:97] op_sel_hi:[1,0]
	v_pk_mul_f32 v[32:33], v[32:33], v[96:97] op_sel_hi:[1,0]
	v_pk_mul_f32 v[30:31], v[30:31], v[96:97] op_sel_hi:[1,0]
	v_pk_mul_f32 v[28:29], v[28:29], v[96:97] op_sel_hi:[1,0]
	v_pk_mul_f32 v[26:27], v[26:27], v[96:97] op_sel_hi:[1,0]
	v_pk_mul_f32 v[24:25], v[24:25], v[96:97] op_sel_hi:[1,0]
	v_pk_mul_f32 v[22:23], v[22:23], v[96:97] op_sel_hi:[1,0]
	v_pk_mul_f32 v[20:21], v[20:21], v[96:97] op_sel_hi:[1,0]
	v_pk_mul_f32 v[18:19], v[18:19], v[96:97] op_sel_hi:[1,0]
; __device__ __forceinline__ unsigned cvtpk(float lo, float hi) { typedef __bf16 b2 __attribute__((ext_vector_type(2))); f32x2 v = {lo, hi}; b2 b = __builtin_convertvector(v, b2); return __builtin_bit_cast(unsigned, b); }
; __device__ __forceinline__ int crow(int r, int hi) { return (r & 3) + 8 * (r >> 2) + 4 * hi; }
;     ...
;         if (__any(need)) { const float mnew = need ? mx : mrun, alpha = __builtin_amdgcn_exp2f(mrun - mnew); mrun = mnew; lrun *= alpha;
; #pragma unroll
;             for (int d = 0; d < 4; ++d)
; #pragma unroll
;                 for (int r = 0; r < 16; ++r) o[d][r] *= alpha; }
;         float rsa[4] = {0.f, 0.f, 0.f, 0.f};
; #pragma unroll
;         for (int r = 0; r < 16; ++r) { float p0 = __builtin_amdgcn_exp2f(s0[r] - mrun), p1 = __builtin_amdgcn_exp2f(s1[r] - mrun);
;             if (LAYER == 1) { const int kv = crow(r, hi); p0 = ((w0 >> kv) & 1u) ? p0 : 0.f; p1 = ((w1 >> kv) & 1u) ? p1 : 0.f; }
;             s0[r] = p0; s1[r] = p1; rsa[r & 3] += p0 + p1; }
;         lrun += (rsa[0] + rsa[1]) + (rsa[2] + rsa[3]);
; #pragma unroll
;         for (int s = 0; s < 2; ++s) {
;             v4u x; x.x = cvtpk(s0[8 * s + 0], s0[8 * s + 1]); x.y = cvtpk(s0[8 * s + 2], s0[8 * s + 3]); x.z = cvtpk(s0[8 * s + 4], s0[8 * s + 5]); x.w = cvtpk(s0[8 * s + 6], s0[8 * s + 7]); pb[0][s] = __builtin_bit_cast(bf16x8, x);
;             v4u y; y.x = cvtpk(s1[8 * s + 0], s1[8 * s + 1]); y.y = cvtpk(s1[8 * s + 2], s1[8 * s + 3]); y.z = cvtpk(s1[8 * s + 4], s1[8 * s + 5]); y.w = cvtpk(s1[8 * s + 6], s1[8 * s + 7]); pb[1][s] = __builtin_bit_cast(bf16x8, y); }
;     ...
;             if (wkb) { vb = sbb + KBUF + vlane; ATT_VREAD(vpre, 0); SM(wb0, wb1, b0, b1, pbb);
;                 ATT_VREAD(va, 1); __builtin_amdgcn_s_setprio(1); ATT_PV(vpre, pbb, 0); __builtin_amdgcn_s_setprio(0);
;                 ATT_VREAD(vbb, 2); __builtin_amdgcn_s_setprio(1); ATT_PV(va, pbb, 1); __builtin_amdgcn_s_setprio(0);
;                 ATT_VREAD(va, 3); __builtin_amdgcn_s_setprio(1); ATT_PV(vbb, pbb, 2); __builtin_amdgcn_s_setprio(0);
;                 __builtin_amdgcn_s_setprio(1); ATT_PV(va, pbb, 3); __builtin_amdgcn_s_setprio(0); }
.LBB0_2117:
	v_max_f32_e32 v246, 0xef800000, v206
	v_sub_f32_e32 v96, v212, v246
	v_sub_f32_e32 v97, v223, v246
	v_exp_f32_e32 v96, v96
	v_exp_f32_e32 v97, v97
	v_sub_f32_e32 v107, v210, v246
	v_sub_f32_e32 v113, v209, v246
	v_sub_f32_e32 v209, v213, v246
	v_sub_f32_e32 v210, v219, v246
	v_exp_f32_e32 v209, v209
	v_exp_f32_e32 v210, v210
	v_sub_f32_e32 v108, v222, v246
	v_add_f32_e32 v109, v96, v97
	v_exp_f32_e32 v107, v107
	v_exp_f32_e32 v108, v108
	v_add_f32_e32 v109, 0, v109
	v_sub_f32_e32 v110, v214, v246
	v_sub_f32_e32 v111, v221, v246
	v_sub_f32_e32 v207, v207, v246
	v_sub_f32_e32 v213, v218, v246
	v_add_f32_e32 v214, v209, v210
	v_exp_f32_e32 v110, v110
	v_exp_f32_e32 v111, v111
	v_sub_f32_e32 v156, v220, v246
	v_exp_f32_e32 v207, v207
	v_exp_f32_e32 v213, v213
	v_add_f32_e32 v109, v214, v109
	v_sub_f32_e32 v211, v211, v246
	v_sub_f32_e32 v214, v217, v246
	v_exp_f32_e32 v113, v113
	v_exp_f32_e32 v156, v156
	v_exp_f32_e32 v211, v211
	v_exp_f32_e32 v214, v214
	v_sub_f32_e32 v208, v208, v246
	v_sub_f32_e32 v215, v215, v246
	v_exp_f32_e32 v208, v208
	v_exp_f32_e32 v215, v215
	v_sub_f32_e32 v90, v90, v246
	v_add_f32_e32 v112, v107, v108
	v_exp_f32_e32 v90, v90
	v_add_f32_e32 v112, 0, v112
	v_add_f32_e32 v157, v110, v111
	v_add_f32_e32 v217, v207, v213
	v_add_f32_e32 v157, 0, v157
	v_add_f32_e32 v212, v113, v156
	v_add_f32_e32 v112, v217, v112
	v_add_f32_e32 v217, v211, v214
	v_sub_f32_e32 v216, v216, v246
	v_add_f32_e32 v212, 0, v212
	v_add_f32_e32 v157, v217, v157
	v_exp_f32_e32 v216, v216
	v_add_f32_e32 v217, v208, v215
	v_add_f32_e32 v212, v217, v212
	v_mov_b32_e32 v217, v90
	v_sub_f32_e32 v90, v105, v246
	v_exp_f32_e32 v90, v90
	v_sub_f32_e32 v105, v106, v246
	v_add_f32_e32 v106, v217, v216
	v_add_f32_e32 v106, v106, v109
	v_mov_b32_e32 v109, v90
	v_sub_f32_e32 v90, v103, v246
	v_exp_f32_e32 v218, v105
	v_exp_f32_e32 v105, v90
	v_sub_f32_e32 v103, v104, v246
	v_exp_f32_e32 v219, v103
	v_sub_f32_e32 v90, v101, v246
	v_exp_f32_e32 v103, v90
	v_sub_f32_e32 v101, v102, v246
	v_exp_f32_e32 v101, v101
	v_sub_f32_e32 v90, v99, v246
	v_exp_f32_e32 v90, v90
	v_sub_f32_e32 v99, v100, v246
	v_add_f32_e32 v102, v105, v219
	v_exp_f32_e32 v220, v99
	v_add_f32_e32 v102, v102, v157
	v_mov_b32_e32 v157, v101
	v_mov_b32_e32 v101, v90
	v_sub_f32_e32 v90, v95, v246
	v_exp_f32_e32 v90, v90
	v_sub_f32_e32 v95, v98, v246
	v_exp_f32_e32 v221, v95
	v_add_f32_e32 v98, v101, v220
	v_add_f32_e32 v98, v98, v106
	v_mov_b32_e32 v106, v90
	v_sub_f32_e32 v90, v93, v246
	v_exp_f32_e32 v90, v90
	v_add_f32_e32 v104, v109, v218
	v_sub_f32_e32 v93, v94, v246
	v_add_f32_e32 v104, v104, v112
	v_exp_f32_e32 v222, v93
	v_add_f32_e32 v94, v106, v221
	v_add_f32_e32 v94, v94, v104
	v_mov_b32_e32 v104, v90
	v_sub_f32_e32 v90, v91, v246
	v_sub_f32_e32 v91, v92, v246
	v_exp_f32_e32 v90, v90
	v_exp_f32_e32 v223, v91
	v_add_f32_e32 v92, v104, v222
	v_add_f32_e32 v100, v103, v157
	v_add_f32_e32 v92, v92, v102
	v_mov_b32_e32 v102, v90
	v_add_f32_e32 v100, v100, v212
	v_add_f32_e32 v90, v102, v223
	v_add_f32_e32 v90, v90, v100
	v_add_f32_e32 v91, v98, v94
	v_add_f32_e32 v90, v92, v90
	v_add_f32_e32 v224, v91, v90
	v_cvt_pk_bf16_f32 v90, v96, v107
	v_cvt_pk_bf16_f32 v91, v110, v113
	v_cvt_pk_bf16_f32 v92, v209, v207
	v_cvt_pk_bf16_f32 v93, v211, v208
	v_cvt_pk_bf16_f32 v94, v97, v108
	v_cvt_pk_bf16_f32 v95, v111, v156
	v_cvt_pk_bf16_f32 v96, v210, v213
	v_cvt_pk_bf16_f32 v98, v217, v109
	v_cvt_pk_bf16_f32 v99, v105, v103
	v_cvt_pk_bf16_f32 v100, v101, v106
	v_cvt_pk_bf16_f32 v101, v104, v102
	ds_read_b64_tr_b16 v[102:103], v155 offset:53248
	ds_read_b64_tr_b16 v[104:105], v199 offset:55296
	ds_read_b64_tr_b16 v[106:107], v200 offset:53248
	ds_read_b64_tr_b16 v[108:109], v201 offset:55296
	ds_read_b64_tr_b16 v[110:111], v202 offset:53248
	ds_read_b64_tr_b16 v[112:113], v203 offset:55296
	ds_read_b64_tr_b16 v[208:209], v204 offset:53248
	ds_read_b64_tr_b16 v[210:211], v205 offset:55296
	v_cvt_pk_bf16_f32 v97, v214, v215
	v_cvt_pk_bf16_f32 v212, v216, v218
	v_cvt_pk_bf16_f32 v213, v219, v157
	v_cvt_pk_bf16_f32 v214, v220, v221
	v_cvt_pk_bf16_f32 v215, v222, v223
	s_setprio 1
	s_waitcnt lgkmcnt(12)
	v_mfma_f32_32x32x16_bf16 v[66:81], v[138:141], v[90:93], v[66:81]
	v_add_f32_e32 v192, v192, v224
	v_mfma_f32_32x32x16_bf16 v[50:65], v[134:137], v[90:93], v[50:65]
	s_waitcnt lgkmcnt(10)
	v_mfma_f32_32x32x16_bf16 v[34:49], v[86:89], v[90:93], v[34:49]
	s_waitcnt lgkmcnt(8)
	v_mfma_f32_32x32x16_bf16 v[18:33], v[82:85], v[90:93], v[18:33]
	s_setprio 0
	ds_read_b64_tr_b16 v[82:83], v155 offset:57344
	ds_read_b64_tr_b16 v[84:85], v199 offset:59392
	ds_read_b64_tr_b16 v[86:87], v200 offset:57344
	ds_read_b64_tr_b16 v[88:89], v201 offset:59392
	ds_read_b64_tr_b16 v[90:91], v202 offset:57344
	ds_read_b64_tr_b16 v[92:93], v203 offset:59392
	ds_read_b64_tr_b16 v[134:135], v204 offset:57344
	ds_read_b64_tr_b16 v[136:137], v205 offset:59392
	s_setprio 1
	s_waitcnt lgkmcnt(14)
	v_mfma_f32_32x32x16_bf16 v[66:81], v[102:105], v[98:101], v[66:81]
	s_waitcnt lgkmcnt(12)
	v_mfma_f32_32x32x16_bf16 v[50:65], v[106:109], v[98:101], v[50:65]
	s_waitcnt lgkmcnt(10)
	v_mfma_f32_32x32x16_bf16 v[34:49], v[110:113], v[98:101], v[34:49]
	s_waitcnt lgkmcnt(8)
	v_mfma_f32_32x32x16_bf16 v[18:33], v[208:211], v[98:101], v[18:33]
	s_setprio 0
	ds_read_b64_tr_b16 v[98:99], v155 offset:61440
	ds_read_b64_tr_b16 v[100:101], v199 offset:63488
	ds_read_b64_tr_b16 v[102:103], v200 offset:61440
	ds_read_b64_tr_b16 v[104:105], v201 offset:63488
	ds_read_b64_tr_b16 v[106:107], v202 offset:61440
	ds_read_b64_tr_b16 v[108:109], v203 offset:63488
	ds_read_b64_tr_b16 v[110:111], v204 offset:61440
	ds_read_b64_tr_b16 v[112:113], v205 offset:63488
	s_setprio 1
	s_waitcnt lgkmcnt(14)
	v_mfma_f32_32x32x16_bf16 v[66:81], v[82:85], v[94:97], v[66:81]
	s_waitcnt lgkmcnt(12)
	v_mfma_f32_32x32x16_bf16 v[50:65], v[86:89], v[94:97], v[50:65]
	s_waitcnt lgkmcnt(10)
	v_mfma_f32_32x32x16_bf16 v[34:49], v[90:93], v[94:97], v[34:49]
	s_waitcnt lgkmcnt(8)
	v_mfma_f32_32x32x16_bf16 v[18:33], v[134:137], v[94:97], v[18:33]
	s_setprio 0
	s_setprio 1
	s_waitcnt lgkmcnt(6)
	v_mfma_f32_32x32x16_bf16 v[66:81], v[98:101], v[212:215], v[66:81]
	s_waitcnt lgkmcnt(4)
	v_mfma_f32_32x32x16_bf16 v[50:65], v[102:105], v[212:215], v[50:65]
	s_waitcnt lgkmcnt(2)
	v_mfma_f32_32x32x16_bf16 v[34:49], v[106:109], v[212:215], v[34:49]
	s_waitcnt lgkmcnt(0)
	v_mfma_f32_32x32x16_bf16 v[18:33], v[110:113], v[212:215], v[18:33]
	s_setprio 0
